# final RMS-norm output stores are plain (write-back) global_store_dwordx4 instead of nt (on top of v15)
# speedup vs baseline: 1.0122x; 1.0122x over previous
.LBB0_1964:
	s_or_b64 exec, exec, s[34:35]
	v_lshlrev_b64 v[146:147], 2, v[146:147]
	s_waitcnt lgkmcnt(0)
	s_barrier
	s_waitcnt lgkmcnt(0)
	v_lshl_add_u64 v[0:1], s[8:9], 0, v[146:147]
	global_load_dwordx4 v[12:15], v[0:1], off
	global_load_dwordx4 v[8:11], v[0:1], off offset:16
	global_load_dwordx4 v[4:7], v[0:1], off offset:512
	s_nop 0
	global_load_dwordx4 v[0:3], v[0:1], off offset:528
	v_lshl_add_u32 v185, v185, 2, 0
	v_add_u32_e32 v185, 0x20000, v185
	ds_read2_b32 v[186:187], v185 offset1:16
	ds_read2_b32 v[188:189], v185 offset0:32 offset1:48
	v_lshlrev_b64 v[144:145], 12, v[144:145]
	v_lshlrev_b64 v[148:149], 12, v[148:149]
	v_lshlrev_b64 v[150:151], 12, v[150:151]
	v_lshl_add_u64 v[144:145], s[10:11], 0, v[144:145]
	s_waitcnt lgkmcnt(1)
	v_pk_mul_f32 v[124:125], v[124:125], v[186:187] op_sel_hi:[1,0]
	v_pk_mul_f32 v[126:127], v[126:127], v[186:187] op_sel_hi:[1,0]
	v_pk_mul_f32 v[120:121], v[120:121], v[186:187] op_sel_hi:[1,0]
	v_pk_mul_f32 v[122:123], v[122:123], v[186:187] op_sel_hi:[1,0]
	v_pk_mul_f32 v[116:117], v[116:117], v[186:187] op_sel_hi:[1,0]
	v_pk_mul_f32 v[118:119], v[118:119], v[186:187] op_sel_hi:[1,0]
	v_pk_mul_f32 v[112:113], v[112:113], v[186:187] op_sel_hi:[1,0]
	v_pk_mul_f32 v[114:115], v[114:115], v[186:187] op_sel_hi:[1,0]
	v_mov_b32_e32 v186, v187
	v_lshl_add_u64 v[148:149], s[10:11], 0, v[148:149]
	v_lshl_add_u64 v[150:151], s[10:11], 0, v[150:151]
	v_lshl_add_u64 v[144:145], v[144:145], 0, v[146:147]
	s_waitcnt lgkmcnt(0)
	v_pk_mul_f32 v[190:191], v[92:93], v[188:189] op_sel_hi:[1,0]
	v_pk_mul_f32 v[192:193], v[94:95], v[188:189] op_sel_hi:[1,0]
	v_pk_mul_f32 v[194:195], v[88:89], v[188:189] op_sel_hi:[1,0]
	v_pk_mul_f32 v[196:197], v[90:91], v[188:189] op_sel_hi:[1,0]
	v_pk_mul_f32 v[198:199], v[84:85], v[188:189] op_sel_hi:[1,0]
	v_pk_mul_f32 v[200:201], v[86:87], v[188:189] op_sel_hi:[1,0]
	v_pk_mul_f32 v[202:203], v[80:81], v[188:189] op_sel_hi:[1,0]
	v_pk_mul_f32 v[204:205], v[82:83], v[188:189] op_sel_hi:[1,0]
	v_pk_mul_f32 v[108:109], v[108:109], v[186:187] op_sel_hi:[1,0]
	v_pk_mul_f32 v[110:111], v[110:111], v[186:187] op_sel_hi:[1,0]
	v_pk_mul_f32 v[104:105], v[104:105], v[186:187] op_sel_hi:[1,0]
	v_pk_mul_f32 v[106:107], v[106:107], v[186:187] op_sel_hi:[1,0]
	v_pk_mul_f32 v[206:207], v[100:101], v[186:187] op_sel_hi:[1,0]
	v_pk_mul_f32 v[208:209], v[102:103], v[186:187] op_sel_hi:[1,0]
	v_pk_mul_f32 v[210:211], v[96:97], v[186:187] op_sel_hi:[1,0]
	v_pk_mul_f32 v[186:187], v[98:99], v[186:187] op_sel_hi:[1,0]
	v_lshlrev_b64 v[152:153], 12, v[152:153]
	v_lshl_add_u64 v[148:149], v[148:149], 0, v[146:147]
	v_lshl_add_u64 v[150:151], v[150:151], 0, v[146:147]
	s_and_b64 vcc, exec, s[4:5]
	s_mov_b64 s[4:5], -1
	s_waitcnt vmcnt(3)
	v_pk_mul_f32 v[82:83], v[14:15], v[126:127]
	v_pk_mul_f32 v[80:81], v[12:13], v[124:125]
	s_waitcnt vmcnt(2)
	v_pk_mul_f32 v[86:87], v[10:11], v[122:123]
	v_pk_mul_f32 v[84:85], v[8:9], v[120:121]
	s_waitcnt vmcnt(1)
	v_pk_mul_f32 v[90:91], v[6:7], v[118:119]
	v_pk_mul_f32 v[88:89], v[4:5], v[116:117]
	s_waitcnt vmcnt(0)
	v_pk_mul_f32 v[94:95], v[2:3], v[114:115]
	v_pk_mul_f32 v[92:93], v[0:1], v[112:113]
	v_pk_mul_f32 v[98:99], v[14:15], v[110:111]
	v_pk_mul_f32 v[96:97], v[12:13], v[108:109]
	v_pk_mul_f32 v[102:103], v[10:11], v[106:107]
	v_pk_mul_f32 v[100:101], v[8:9], v[104:105]
	v_pk_mul_f32 v[106:107], v[6:7], v[208:209]
	v_pk_mul_f32 v[104:105], v[4:5], v[206:207]
	v_pk_mul_f32 v[110:111], v[2:3], v[186:187]
	v_pk_mul_f32 v[108:109], v[0:1], v[210:211]
	v_pk_mul_f32 v[114:115], v[14:15], v[192:193]
	v_pk_mul_f32 v[112:113], v[12:13], v[190:191]
	v_pk_mul_f32 v[118:119], v[10:11], v[196:197]
	v_pk_mul_f32 v[116:117], v[8:9], v[194:195]
	v_pk_mul_f32 v[122:123], v[6:7], v[200:201]
	v_pk_mul_f32 v[120:121], v[4:5], v[198:199]
	v_pk_mul_f32 v[126:127], v[2:3], v[204:205]
	v_pk_mul_f32 v[124:125], v[0:1], v[202:203]
	global_store_dwordx4 v[144:145], v[80:83], off
	global_store_dwordx4 v[144:145], v[84:87], off offset:16
	global_store_dwordx4 v[144:145], v[88:91], off offset:512
	global_store_dwordx4 v[144:145], v[92:95], off offset:528
	global_store_dwordx4 v[148:149], v[96:99], off
	global_store_dwordx4 v[148:149], v[100:103], off offset:16
	global_store_dwordx4 v[148:149], v[104:107], off offset:512
	global_store_dwordx4 v[148:149], v[108:111], off offset:528
	global_store_dwordx4 v[150:151], v[112:115], off
	global_store_dwordx4 v[150:151], v[116:119], off offset:16
	global_store_dwordx4 v[150:151], v[120:123], off offset:512
	global_store_dwordx4 v[150:151], v[124:127], off offset:528
	v_mov_b32_e32 v82, v189
	v_lshl_add_u64 v[80:81], s[10:11], 0, v[152:153]
	v_pk_mul_f32 v[68:69], v[68:69], v[82:83] op_sel_hi:[1,0]
	v_pk_mul_f32 v[70:71], v[70:71], v[82:83] op_sel_hi:[1,0]
	v_lshl_add_u64 v[80:81], v[80:81], 0, v[146:147]
	v_pk_mul_f32 v[70:71], v[6:7], v[70:71]
	v_pk_mul_f32 v[68:69], v[4:5], v[68:69]
	global_store_dwordx4 v[80:81], v[68:71], off offset:512
	ds_read2_b32 v[68:69], v185 offset0:128 offset1:144
	v_pk_mul_f32 v[64:65], v[64:65], v[82:83] op_sel_hi:[1,0]
	v_pk_mul_f32 v[66:67], v[66:67], v[82:83] op_sel_hi:[1,0]
	v_pk_mul_f32 v[64:65], v[0:1], v[64:65]
	v_pk_mul_f32 v[66:67], v[2:3], v[66:67]
	global_store_dwordx4 v[80:81], v[64:67], off offset:528
	s_waitcnt lgkmcnt(0)
	v_pk_mul_f32 v[48:49], v[48:49], v[68:69] op_sel_hi:[1,0]
	v_pk_mul_f32 v[50:51], v[50:51], v[68:69] op_sel_hi:[1,0]
	v_lshlrev_b64 v[64:65], 12, v[154:155]
	v_lshl_add_u64 v[64:65], s[10:11], 0, v[64:65]
	v_lshl_add_u64 v[64:65], v[64:65], 0, v[146:147]
	v_pk_mul_f32 v[50:51], v[2:3], v[50:51]
	v_pk_mul_f32 v[48:49], v[0:1], v[48:49]
	global_store_dwordx4 v[64:65], v[48:51], off offset:528
	v_pk_mul_f32 v[52:53], v[52:53], v[68:69] op_sel_hi:[1,0]
	v_pk_mul_f32 v[54:55], v[54:55], v[68:69] op_sel_hi:[1,0]
	v_lshlrev_b64 v[48:49], 12, v[156:157]
	v_mov_b32_e32 v50, v69
	v_lshl_add_u64 v[48:49], s[10:11], 0, v[48:49]
	v_pk_mul_f32 v[36:37], v[36:37], v[50:51] op_sel_hi:[1,0]
	v_pk_mul_f32 v[38:39], v[38:39], v[50:51] op_sel_hi:[1,0]
	v_pk_mul_f32 v[54:55], v[6:7], v[54:55]
	v_pk_mul_f32 v[52:53], v[4:5], v[52:53]
	v_lshl_add_u64 v[48:49], v[48:49], 0, v[146:147]
	v_pk_mul_f32 v[38:39], v[6:7], v[38:39]
	v_pk_mul_f32 v[36:37], v[4:5], v[36:37]
	global_store_dwordx4 v[64:65], v[52:55], off offset:512
	global_store_dwordx4 v[48:49], v[36:39], off offset:512
	ds_read2_b32 v[36:37], v185 offset0:160 offset1:176
	v_pk_mul_f32 v[32:33], v[32:33], v[50:51] op_sel_hi:[1,0]
	v_pk_mul_f32 v[34:35], v[34:35], v[50:51] op_sel_hi:[1,0]
	v_pk_mul_f32 v[32:33], v[0:1], v[32:33]
	v_pk_mul_f32 v[34:35], v[2:3], v[34:35]
	global_store_dwordx4 v[48:49], v[32:35], off offset:528
	s_waitcnt lgkmcnt(0)
	v_pk_mul_f32 v[16:17], v[16:17], v[36:37] op_sel_hi:[1,0]
	v_pk_mul_f32 v[18:19], v[18:19], v[36:37] op_sel_hi:[1,0]
	v_lshlrev_b64 v[32:33], 12, v[158:159]
	v_lshl_add_u64 v[32:33], s[10:11], 0, v[32:33]
	v_lshl_add_u64 v[32:33], v[32:33], 0, v[146:147]
	v_pk_mul_f32 v[20:21], v[20:21], v[36:37] op_sel_hi:[1,0]
	v_pk_mul_f32 v[22:23], v[22:23], v[36:37] op_sel_hi:[1,0]
	v_pk_mul_f32 v[18:19], v[2:3], v[18:19]
	v_pk_mul_f32 v[16:17], v[0:1], v[16:17]
	v_pk_mul_f32 v[22:23], v[6:7], v[22:23]
	v_pk_mul_f32 v[20:21], v[4:5], v[20:21]
	global_store_dwordx4 v[32:33], v[16:19], off offset:528
	v_pk_mul_f32 v[76:77], v[76:77], v[82:83] op_sel_hi:[1,0]
	v_pk_mul_f32 v[78:79], v[78:79], v[82:83] op_sel_hi:[1,0]
	v_lshlrev_b64 v[16:17], 12, v[160:161]
	v_mov_b32_e32 v18, v37
	v_pk_mul_f32 v[60:61], v[60:61], v[68:69] op_sel_hi:[1,0]
	v_pk_mul_f32 v[62:63], v[62:63], v[68:69] op_sel_hi:[1,0]
	v_pk_mul_f32 v[44:45], v[44:45], v[50:51] op_sel_hi:[1,0]
	v_pk_mul_f32 v[46:47], v[46:47], v[50:51] op_sel_hi:[1,0]
	v_pk_mul_f32 v[28:29], v[28:29], v[36:37] op_sel_hi:[1,0]
	v_pk_mul_f32 v[30:31], v[30:31], v[36:37] op_sel_hi:[1,0]
	global_store_dwordx4 v[32:33], v[20:23], off offset:512
	v_lshl_add_u64 v[16:17], s[10:11], 0, v[16:17]
	v_pk_mul_f32 v[78:79], v[14:15], v[78:79]
	v_pk_mul_f32 v[20:21], v[176:177], v[18:19] op_sel_hi:[1,0]
	v_pk_mul_f32 v[22:23], v[174:175], v[18:19] op_sel_hi:[1,0]
	v_pk_mul_f32 v[76:77], v[12:13], v[76:77]
	v_pk_mul_f32 v[62:63], v[14:15], v[62:63]
	v_pk_mul_f32 v[60:61], v[12:13], v[60:61]
	v_pk_mul_f32 v[46:47], v[14:15], v[46:47]
	v_pk_mul_f32 v[44:45], v[12:13], v[44:45]
	v_pk_mul_f32 v[30:31], v[14:15], v[30:31]
	v_pk_mul_f32 v[28:29], v[12:13], v[28:29]
	v_lshl_add_u64 v[16:17], v[16:17], 0, v[146:147]
	v_pk_mul_f32 v[14:15], v[14:15], v[22:23]
	v_pk_mul_f32 v[12:13], v[12:13], v[20:21]
	global_store_dwordx4 v[80:81], v[76:79], off
	v_pk_mul_f32 v[72:73], v[72:73], v[82:83] op_sel_hi:[1,0]
	v_pk_mul_f32 v[74:75], v[74:75], v[82:83] op_sel_hi:[1,0]
	global_store_dwordx4 v[64:65], v[60:63], off
	v_pk_mul_f32 v[56:57], v[56:57], v[68:69] op_sel_hi:[1,0]
	v_pk_mul_f32 v[58:59], v[58:59], v[68:69] op_sel_hi:[1,0]
	global_store_dwordx4 v[48:49], v[44:47], off
	v_pk_mul_f32 v[40:41], v[40:41], v[50:51] op_sel_hi:[1,0]
	v_pk_mul_f32 v[42:43], v[42:43], v[50:51] op_sel_hi:[1,0]
	global_store_dwordx4 v[32:33], v[28:31], off
	v_pk_mul_f32 v[24:25], v[24:25], v[36:37] op_sel_hi:[1,0]
	v_pk_mul_f32 v[26:27], v[26:27], v[36:37] op_sel_hi:[1,0]
	global_store_dwordx4 v[16:17], v[12:15], off
	v_pk_mul_f32 v[74:75], v[10:11], v[74:75]
	v_pk_mul_f32 v[72:73], v[8:9], v[72:73]
	v_pk_mul_f32 v[12:13], v[172:173], v[18:19] op_sel_hi:[1,0]
	v_pk_mul_f32 v[14:15], v[170:171], v[18:19] op_sel_hi:[1,0]
	v_pk_mul_f32 v[58:59], v[10:11], v[58:59]
	v_pk_mul_f32 v[56:57], v[8:9], v[56:57]
	v_pk_mul_f32 v[42:43], v[10:11], v[42:43]
	v_pk_mul_f32 v[40:41], v[8:9], v[40:41]
	v_pk_mul_f32 v[26:27], v[10:11], v[26:27]
	v_pk_mul_f32 v[24:25], v[8:9], v[24:25]
	v_pk_mul_f32 v[10:11], v[10:11], v[14:15]
	v_pk_mul_f32 v[8:9], v[8:9], v[12:13]
	global_store_dwordx4 v[80:81], v[72:75], off offset:16
	global_store_dwordx4 v[64:65], v[56:59], off offset:16
	global_store_dwordx4 v[48:49], v[40:43], off offset:16
	global_store_dwordx4 v[32:33], v[24:27], off offset:16
	global_store_dwordx4 v[16:17], v[8:11], off offset:16
	s_nop 1
	v_pk_mul_f32 v[8:9], v[168:169], v[18:19] op_sel_hi:[1,0]
	v_pk_mul_f32 v[10:11], v[164:165], v[18:19] op_sel_hi:[1,0]
	v_pk_mul_f32 v[4:5], v[4:5], v[8:9]
	v_pk_mul_f32 v[6:7], v[6:7], v[10:11]
	global_store_dwordx4 v[16:17], v[4:7], off offset:512
	s_nop 1
	v_pk_mul_f32 v[4:5], v[166:167], v[18:19] op_sel_hi:[1,0]
	v_pk_mul_f32 v[6:7], v[162:163], v[18:19] op_sel_hi:[1,0]
	v_pk_mul_f32 v[0:1], v[0:1], v[4:5]
	v_pk_mul_f32 v[2:3], v[2:3], v[6:7]
	global_store_dwordx4 v[16:17], v[0:3], off offset:528
	s_cbranch_vccnz .LBB0_1919
	s_andn2_b64 vcc, exec, s[18:19]
	s_cbranch_vccnz .LBB0_1918
	s_barrier
	s_branch .LBB0_1918
